# v14 + GEMM loop: setprio 1/0 moved outside the MFMA segments (before first / after second barrier), redundant lgkmcnt(0) at MFMA segment head removed
# speedup vs baseline: 1.0180x; 1.0024x over previous
; #define PG8_STAGE(bufoff, gbase, voff) do { _Pragma("unroll") for (int _i = 0; _i < 2; ++_i) \
;     __builtin_amdgcn_global_load_lds((const unsigned*)((const char*)(gbase) + (voff)[_i]), (LAS unsigned*)(lds + (bufoff) + ldsw + _i * 8192), 16, 0, 0); } while (0)
; #define PG8_LDA(dst, b, h) do { _Pragma("unroll") for (int m = 0; m < 4; ++m) _Pragma("unroll") for (int k = 0; k < 2; ++k) dst[m][k] = *(const LAS bf16x8*)(lds + PG8_SA(b, h) + aoff + m * 2048 + k * 1024); } while (0)
; #define PG8_LDB(dst, b, h) do { _Pragma("unroll") for (int n = 0; n < 2; ++n) _Pragma("unroll") for (int k = 0; k < 2; ++k) dst[n][k] = *(const LAS bf16x8*)(lds + PG8_SB(b, h) + boff + n * 2048 + k * 1024); } while (0)
; #define PG8_MMA(ai, bj, At, Bt) do { __builtin_amdgcn_s_setprio(1); _Pragma("unroll") for (int m = 0; m < 4; ++m) _Pragma("unroll") for (int n = 0; n < 2; ++n) _Pragma("unroll") for (int k = 0; k < 2; ++k) \
;     acc[ai][bj][m][n] = __builtin_amdgcn_mfma_f32_16x16x32_bf16(Bt[n][k], At[m][k], acc[ai][bj][m][n], 0, 0, 0); __builtin_amdgcn_s_setprio(0); } while (0)
; #define PG8_WAIT_V(n) asm volatile("s_waitcnt vmcnt(" #n ")" ::: "memory")
; #define PG8_WAIT_L(n) asm volatile("s_waitcnt lgkmcnt(" #n ")" ::: "memory")
; #define PG8_BAR __builtin_amdgcn_s_barrier()
; #define PG8_SCHED __builtin_amdgcn_sched_barrier(0)
; DI void gemm_phase(const GemmDesc& g, LAS unsigned char* lds) {
;     ...
;       PG8_LDB(B0, 0, 0); PG8_LDB(B1, 0, 1); PG8_SCHED; PG8_LDA(At, 0, 0); PG8_STAGE(PG8_SA(1, 1), a1 + hstep, voffA);
;       PG8_WAIT_V(8); PG8_WAIT_L(0); PG8_BAR; PG8_MMA(0, 0, At, B0); PG8_MMA(0, 1, At, B1); PG8_BAR; PG8_SCHED;
;       PG8_LDA(At, 0, 1); PG8_STAGE(PG8_SB(0, 0), b2, voffB); PG8_STAGE(PG8_SB(0, 1), b2 + hstep, voffB); PG8_STAGE(PG8_SA(0, 0), a2, voffA);
;       PG8_WAIT_V(8); PG8_WAIT_L(0); PG8_BAR; PG8_MMA(1, 0, At, B0); PG8_MMA(1, 1, At, B1); PG8_BAR; PG8_SCHED;
.LBB0_132:
	ds_read_b128 v[128:131], v250
	ds_read_b128 v[132:135], v250 offset:1024
	ds_read_b128 v[136:139], v250 offset:2048
	ds_read_b128 v[140:143], v250 offset:3072
	ds_read_b128 v[164:167], v250 offset:16384
	ds_read_b128 v[168:171], v250 offset:17408
	ds_read_b128 v[172:175], v250 offset:18432
	ds_read_b128 v[176:179], v250 offset:19456
	s_add_i32 m0, s73, 0xc000
	ds_read_b128 v[180:183], v228
	ds_read_b128 v[184:187], v228 offset:1024
	ds_read_b128 v[188:191], v228 offset:2048
	ds_read_b128 v[192:195], v228 offset:3072
	ds_read_b128 v[196:199], v228 offset:4096
	ds_read_b128 v[200:203], v228 offset:5120
	ds_read_b128 v[230:233], v228 offset:6144
	ds_read_b128 v[234:237], v228 offset:7168
	global_load_lds_dwordx4 v162, s[26:27]
	s_add_i32 m0, s73, 0xe000
	s_nop 0
	global_load_lds_dwordx4 v160, s[26:27]
	s_add_i32 s48, s44, 2
	s_add_u32 s49, s26, 0x80
	s_addc_u32 s45, s27, 0
	s_add_i32 s51, 0, 0x10000
	s_cmp_eq_u32 s94, s44
	s_cselect_b32 s45, s63, s45
	s_cselect_b32 s44, s62, s49
	s_cselect_b32 s87, s1, s47
	s_cselect_b32 s86, s0, s46
	s_add_i32 s49, 0, 0x14000
	s_waitcnt vmcnt(8)
	s_waitcnt lgkmcnt(0)
	s_setprio 1
	s_barrier
	v_mfma_f32_16x16x32_bf16 v[124:127], v[128:131], v[180:183], v[124:127]
	v_mfma_f32_16x16x32_bf16 v[120:123], v[136:139], v[180:183], v[120:123]
	v_mfma_f32_16x16x32_bf16 v[116:119], v[128:131], v[188:191], v[116:119]
	v_mfma_f32_16x16x32_bf16 v[112:115], v[136:139], v[188:191], v[112:115]
	v_mfma_f32_16x16x32_bf16 v[108:111], v[128:131], v[196:199], v[108:111]
	v_mfma_f32_16x16x32_bf16 v[104:107], v[136:139], v[196:199], v[104:107]
	v_mfma_f32_16x16x32_bf16 v[100:103], v[128:131], v[230:233], v[100:103]
	v_mfma_f32_16x16x32_bf16 v[96:99], v[136:139], v[230:233], v[96:99]
	v_mfma_f32_16x16x32_bf16 v[124:127], v[132:135], v[184:187], v[124:127]
	v_mfma_f32_16x16x32_bf16 v[120:123], v[140:143], v[184:187], v[120:123]
	v_mfma_f32_16x16x32_bf16 v[116:119], v[132:135], v[192:195], v[116:119]
	v_mfma_f32_16x16x32_bf16 v[112:115], v[140:143], v[192:195], v[112:115]
	v_mfma_f32_16x16x32_bf16 v[108:111], v[132:135], v[200:203], v[108:111]
	v_mfma_f32_16x16x32_bf16 v[104:107], v[140:143], v[200:203], v[104:107]
	v_mfma_f32_16x16x32_bf16 v[100:103], v[132:135], v[234:237], v[100:103]
	v_mfma_f32_16x16x32_bf16 v[96:99], v[140:143], v[234:237], v[96:99]
	v_mfma_f32_16x16x32_bf16 v[60:63], v[164:167], v[180:183], v[60:63]
	v_mfma_f32_16x16x32_bf16 v[56:59], v[172:175], v[180:183], v[56:59]
	v_mfma_f32_16x16x32_bf16 v[52:55], v[164:167], v[188:191], v[52:55]
	v_mfma_f32_16x16x32_bf16 v[48:51], v[172:175], v[188:191], v[48:51]
	v_mfma_f32_16x16x32_bf16 v[44:47], v[164:167], v[196:199], v[44:47]
	v_mfma_f32_16x16x32_bf16 v[40:43], v[172:175], v[196:199], v[40:43]
	v_mfma_f32_16x16x32_bf16 v[36:39], v[164:167], v[230:233], v[36:39]
	v_mfma_f32_16x16x32_bf16 v[32:35], v[172:175], v[230:233], v[32:35]
	v_mfma_f32_16x16x32_bf16 v[60:63], v[168:171], v[184:187], v[60:63]
	v_mfma_f32_16x16x32_bf16 v[56:59], v[176:179], v[184:187], v[56:59]
	v_mfma_f32_16x16x32_bf16 v[52:55], v[168:171], v[192:195], v[52:55]
	v_mfma_f32_16x16x32_bf16 v[48:51], v[176:179], v[192:195], v[48:51]
	v_mfma_f32_16x16x32_bf16 v[44:47], v[168:171], v[200:203], v[44:47]
	v_mfma_f32_16x16x32_bf16 v[40:43], v[176:179], v[200:203], v[40:43]
	v_mfma_f32_16x16x32_bf16 v[36:39], v[168:171], v[234:237], v[36:39]
	v_mfma_f32_16x16x32_bf16 v[32:35], v[176:179], v[234:237], v[32:35]
	s_barrier
	s_setprio 0
	s_add_i32 s51, s51, s72
	s_mov_b32 m0, s51
	ds_read_b128 v[180:183], v228 offset:16384
	ds_read_b128 v[184:187], v228 offset:17408
	ds_read_b128 v[188:191], v228 offset:18432
	ds_read_b128 v[192:195], v228 offset:19456
	ds_read_b128 v[196:199], v228 offset:20480
	ds_read_b128 v[200:203], v228 offset:21504
	ds_read_b128 v[230:233], v228 offset:22528
	ds_read_b128 v[234:237], v228 offset:23552
	global_load_lds_dwordx4 v152, s[86:87]
	s_mov_b64 s[98:99], s[86:87]
	s_add_i32 m0, s51, 0x2000
	s_add_u32 s86, s86, s20
	s_addc_u32 s87, s87, s21
	s_add_i32 s49, s49, s72
	global_load_lds_dwordx4 v156, s[98:99]
	s_mov_b32 m0, s49
	s_nop 0
	global_load_lds_dwordx4 v152, s[86:87]
	s_add_i32 m0, s49, 0x2000
	s_nop 0
	global_load_lds_dwordx4 v156, s[86:87]
	s_mov_b32 m0, s73
	s_nop 0
	s_mov_b64 s[100:101], s[44:45]
	global_load_lds_dwordx4 v150, s[44:45]
	s_mov_b32 m0, s60
	s_nop 0
	global_load_lds_dwordx4 v154, s[44:45]
	s_waitcnt vmcnt(8)
	s_waitcnt lgkmcnt(0)
	s_setprio 1
	s_barrier
	v_mfma_f32_16x16x32_bf16 v[92:95], v[128:131], v[180:183], v[92:95]
	v_mfma_f32_16x16x32_bf16 v[88:91], v[136:139], v[180:183], v[88:91]
	v_mfma_f32_16x16x32_bf16 v[84:87], v[128:131], v[188:191], v[84:87]
	v_mfma_f32_16x16x32_bf16 v[80:83], v[136:139], v[188:191], v[80:83]
	v_mfma_f32_16x16x32_bf16 v[76:79], v[128:131], v[196:199], v[76:79]
	v_mfma_f32_16x16x32_bf16 v[72:75], v[136:139], v[196:199], v[72:75]
	v_mfma_f32_16x16x32_bf16 v[68:71], v[128:131], v[230:233], v[68:71]
	v_mfma_f32_16x16x32_bf16 v[64:67], v[136:139], v[230:233], v[64:67]
	v_mfma_f32_16x16x32_bf16 v[92:95], v[132:135], v[184:187], v[92:95]
	v_mfma_f32_16x16x32_bf16 v[88:91], v[140:143], v[184:187], v[88:91]
	v_mfma_f32_16x16x32_bf16 v[84:87], v[132:135], v[192:195], v[84:87]
	v_mfma_f32_16x16x32_bf16 v[80:83], v[140:143], v[192:195], v[80:83]
	v_mfma_f32_16x16x32_bf16 v[76:79], v[132:135], v[200:203], v[76:79]
	v_mfma_f32_16x16x32_bf16 v[72:75], v[140:143], v[200:203], v[72:75]
	v_mfma_f32_16x16x32_bf16 v[68:71], v[132:135], v[234:237], v[68:71]
	v_mfma_f32_16x16x32_bf16 v[64:67], v[140:143], v[234:237], v[64:67]
	v_mfma_f32_16x16x32_bf16 v[28:31], v[164:167], v[180:183], v[28:31]
	v_mfma_f32_16x16x32_bf16 v[24:27], v[172:175], v[180:183], v[24:27]
	v_mfma_f32_16x16x32_bf16 v[20:23], v[164:167], v[188:191], v[20:23]
	v_mfma_f32_16x16x32_bf16 v[16:19], v[172:175], v[188:191], v[16:19]
	v_mfma_f32_16x16x32_bf16 v[12:15], v[164:167], v[196:199], v[12:15]
	v_mfma_f32_16x16x32_bf16 v[8:11], v[172:175], v[196:199], v[8:11]
	v_mfma_f32_16x16x32_bf16 v[4:7], v[164:167], v[230:233], v[4:7]
	v_mfma_f32_16x16x32_bf16 v[0:3], v[172:175], v[230:233], v[0:3]
	v_mfma_f32_16x16x32_bf16 v[28:31], v[168:171], v[184:187], v[28:31]
	v_mfma_f32_16x16x32_bf16 v[24:27], v[176:179], v[184:187], v[24:27]
	v_mfma_f32_16x16x32_bf16 v[20:23], v[168:171], v[192:195], v[20:23]
	v_mfma_f32_16x16x32_bf16 v[16:19], v[176:179], v[192:195], v[16:19]
	v_mfma_f32_16x16x32_bf16 v[12:15], v[168:171], v[200:203], v[12:15]
	v_mfma_f32_16x16x32_bf16 v[8:11], v[176:179], v[200:203], v[8:11]
	v_mfma_f32_16x16x32_bf16 v[4:7], v[168:171], v[234:237], v[4:7]
	v_mfma_f32_16x16x32_bf16 v[0:3], v[176:179], v[234:237], v[0:3]
	s_barrier
; #define PG8_STAGE(bufoff, gbase, voff) do { _Pragma("unroll") for (int _i = 0; _i < 2; ++_i) \
;     __builtin_amdgcn_global_load_lds((const unsigned*)((const char*)(gbase) + (voff)[_i]), (LAS unsigned*)(lds + (bufoff) + ldsw + _i * 8192), 16, 0, 0); } while (0)
; #define PG8_LDA(dst, b, h) do { _Pragma("unroll") for (int m = 0; m < 4; ++m) _Pragma("unroll") for (int k = 0; k < 2; ++k) dst[m][k] = *(const LAS bf16x8*)(lds + PG8_SA(b, h) + aoff + m * 2048 + k * 1024); } while (0)
; #define PG8_LDB(dst, b, h) do { _Pragma("unroll") for (int n = 0; n < 2; ++n) _Pragma("unroll") for (int k = 0; k < 2; ++k) dst[n][k] = *(const LAS bf16x8*)(lds + PG8_SB(b, h) + boff + n * 2048 + k * 1024); } while (0)
; #define PG8_MMA(ai, bj, At, Bt) do { __builtin_amdgcn_s_setprio(1); _Pragma("unroll") for (int m = 0; m < 4; ++m) _Pragma("unroll") for (int n = 0; n < 2; ++n) _Pragma("unroll") for (int k = 0; k < 2; ++k) \
;     acc[ai][bj][m][n] = __builtin_amdgcn_mfma_f32_16x16x32_bf16(Bt[n][k], At[m][k], acc[ai][bj][m][n], 0, 0, 0); __builtin_amdgcn_s_setprio(0); } while (0)
; #define PG8_WAIT_V(n) asm volatile("s_waitcnt vmcnt(" #n ")" ::: "memory")
; #define PG8_WAIT_L(n) asm volatile("s_waitcnt lgkmcnt(" #n ")" ::: "memory")
; #define PG8_BAR __builtin_amdgcn_s_barrier()
; #define PG8_SCHED __builtin_amdgcn_sched_barrier(0)
; DI void gemm_phase(const GemmDesc& g, LAS unsigned char* lds) {
;     ...
;       PG8_LDB(B0, 1, 0); PG8_LDB(B1, 1, 1); PG8_SCHED; PG8_LDA(At, 1, 0); PG8_STAGE(PG8_SA(0, 1), a2 + hstep, voffA);
;       PG8_WAIT_V(8); PG8_WAIT_L(0); PG8_BAR; PG8_MMA(0, 0, At, B0); PG8_MMA(0, 1, At, B1); PG8_BAR; PG8_SCHED;
;       PG8_LDA(At, 1, 1); PG8_STAGE(PG8_SB(1, 0), b3, voffB); PG8_STAGE(PG8_SB(1, 1), b3 + hstep, voffB); PG8_STAGE(PG8_SA(1, 0), a3, voffA);
;       PG8_WAIT_V(8); PG8_WAIT_L(0); PG8_BAR; PG8_MMA(1, 0, At, B0); PG8_MMA(1, 1, At, B1); PG8_BAR; PG8_SCHED;
;     }
;     if (wr == 0) PG8_BAR;
	s_setprio 0
	ds_read_b128 v[128:131], v250 offset:32768
	ds_read_b128 v[132:135], v250 offset:33792
	ds_read_b128 v[136:139], v250 offset:34816
	ds_read_b128 v[140:143], v250 offset:35840
	ds_read_b128 v[164:167], v250 offset:49152
	ds_read_b128 v[168:171], v250 offset:50176
	ds_read_b128 v[172:175], v250 offset:51200
	ds_read_b128 v[176:179], v250 offset:52224
	s_add_u32 s44, s44, s20
	s_addc_u32 s45, s45, s21
	s_mov_b32 m0, s61
	ds_read_b128 v[180:183], v228 offset:32768
	ds_read_b128 v[184:187], v228 offset:33792
	ds_read_b128 v[188:191], v228 offset:34816
	ds_read_b128 v[192:195], v228 offset:35840
	ds_read_b128 v[196:199], v228 offset:36864
	ds_read_b128 v[200:203], v228 offset:37888
	ds_read_b128 v[230:233], v228 offset:38912
	ds_read_b128 v[234:237], v228 offset:39936
	global_load_lds_dwordx4 v150, s[44:45]
	s_mov_b32 m0, s93
	s_nop 0
	global_load_lds_dwordx4 v154, s[44:45]
	s_add_i32 s49, 0, 0x18000
	s_add_i32 s51, 0, 0x1c000
	s_waitcnt vmcnt(8)
	s_waitcnt lgkmcnt(0)
	s_setprio 1
	s_barrier
	v_mfma_f32_16x16x32_bf16 v[124:127], v[128:131], v[180:183], v[124:127]
	v_mfma_f32_16x16x32_bf16 v[120:123], v[136:139], v[180:183], v[120:123]
	v_mfma_f32_16x16x32_bf16 v[116:119], v[128:131], v[188:191], v[116:119]
	v_mfma_f32_16x16x32_bf16 v[112:115], v[136:139], v[188:191], v[112:115]
	v_mfma_f32_16x16x32_bf16 v[108:111], v[128:131], v[196:199], v[108:111]
	v_mfma_f32_16x16x32_bf16 v[104:107], v[136:139], v[196:199], v[104:107]
	v_mfma_f32_16x16x32_bf16 v[100:103], v[128:131], v[230:233], v[100:103]
	v_mfma_f32_16x16x32_bf16 v[96:99], v[136:139], v[230:233], v[96:99]
	v_mfma_f32_16x16x32_bf16 v[124:127], v[132:135], v[184:187], v[124:127]
	v_mfma_f32_16x16x32_bf16 v[120:123], v[140:143], v[184:187], v[120:123]
	v_mfma_f32_16x16x32_bf16 v[116:119], v[132:135], v[192:195], v[116:119]
	v_mfma_f32_16x16x32_bf16 v[112:115], v[140:143], v[192:195], v[112:115]
	v_mfma_f32_16x16x32_bf16 v[108:111], v[132:135], v[200:203], v[108:111]
	v_mfma_f32_16x16x32_bf16 v[104:107], v[140:143], v[200:203], v[104:107]
	v_mfma_f32_16x16x32_bf16 v[100:103], v[132:135], v[234:237], v[100:103]
	v_mfma_f32_16x16x32_bf16 v[96:99], v[140:143], v[234:237], v[96:99]
	v_mfma_f32_16x16x32_bf16 v[60:63], v[164:167], v[180:183], v[60:63]
	v_mfma_f32_16x16x32_bf16 v[56:59], v[172:175], v[180:183], v[56:59]
	v_mfma_f32_16x16x32_bf16 v[52:55], v[164:167], v[188:191], v[52:55]
	v_mfma_f32_16x16x32_bf16 v[48:51], v[172:175], v[188:191], v[48:51]
	v_mfma_f32_16x16x32_bf16 v[44:47], v[164:167], v[196:199], v[44:47]
	v_mfma_f32_16x16x32_bf16 v[40:43], v[172:175], v[196:199], v[40:43]
	v_mfma_f32_16x16x32_bf16 v[36:39], v[164:167], v[230:233], v[36:39]
	v_mfma_f32_16x16x32_bf16 v[32:35], v[172:175], v[230:233], v[32:35]
	v_mfma_f32_16x16x32_bf16 v[60:63], v[168:171], v[184:187], v[60:63]
	v_mfma_f32_16x16x32_bf16 v[56:59], v[176:179], v[184:187], v[56:59]
	v_mfma_f32_16x16x32_bf16 v[52:55], v[168:171], v[192:195], v[52:55]
	v_mfma_f32_16x16x32_bf16 v[48:51], v[176:179], v[192:195], v[48:51]
	v_mfma_f32_16x16x32_bf16 v[44:47], v[168:171], v[200:203], v[44:47]
	v_mfma_f32_16x16x32_bf16 v[40:43], v[176:179], v[200:203], v[40:43]
	v_mfma_f32_16x16x32_bf16 v[36:39], v[168:171], v[234:237], v[36:39]
	v_mfma_f32_16x16x32_bf16 v[32:35], v[176:179], v[234:237], v[32:35]
	s_barrier
	s_setprio 0
	s_add_i32 s44, s49, s72
	s_sub_i32 m0, s44, 0x80
	ds_read_b128 v[180:183], v228 offset:49152
	ds_read_b128 v[184:187], v228 offset:50176
	ds_read_b128 v[188:191], v228 offset:51200
	ds_read_b128 v[192:195], v228 offset:52224
	ds_read_b128 v[196:199], v228 offset:53248
	ds_read_b128 v[200:203], v228 offset:54272
	ds_read_b128 v[230:233], v228 offset:55296
	ds_read_b128 v[234:237], v228 offset:56320
	global_load_lds_dwordx4 v152, s[98:99] offset:128
	s_add_i32 m0, s44, 0x1f80
	s_add_i32 s44, s51, s72
	global_load_lds_dwordx4 v156, s[98:99] offset:128
	s_sub_i32 m0, s44, 0x80
	s_nop 0
	global_load_lds_dwordx4 v152, s[86:87] offset:128
	s_add_i32 m0, s44, 0x1f80
	s_nop 0
	global_load_lds_dwordx4 v156, s[86:87] offset:128
	s_sub_i32 m0, s95, 0x80
	s_nop 0
	global_load_lds_dwordx4 v150, s[100:101] offset:128
	s_sub_i32 m0, s96, 0x80
	s_nop 0
	global_load_lds_dwordx4 v154, s[100:101] offset:128
	s_add_u32 s46, s46, 0x100
	s_addc_u32 s47, s47, 0
	s_add_u32 s26, s26, 0x100
	s_addc_u32 s27, s27, 0
	s_waitcnt vmcnt(8)
	s_waitcnt lgkmcnt(0)
	s_setprio 1
	s_barrier
	v_mfma_f32_16x16x32_bf16 v[92:95], v[128:131], v[180:183], v[92:95]
	v_mfma_f32_16x16x32_bf16 v[88:91], v[136:139], v[180:183], v[88:91]
	v_mfma_f32_16x16x32_bf16 v[84:87], v[128:131], v[188:191], v[84:87]
	v_mfma_f32_16x16x32_bf16 v[80:83], v[136:139], v[188:191], v[80:83]
	v_mfma_f32_16x16x32_bf16 v[76:79], v[128:131], v[196:199], v[76:79]
	v_mfma_f32_16x16x32_bf16 v[72:75], v[136:139], v[196:199], v[72:75]
	v_mfma_f32_16x16x32_bf16 v[68:71], v[128:131], v[230:233], v[68:71]
	v_mfma_f32_16x16x32_bf16 v[64:67], v[136:139], v[230:233], v[64:67]
	v_mfma_f32_16x16x32_bf16 v[92:95], v[132:135], v[184:187], v[92:95]
	v_mfma_f32_16x16x32_bf16 v[88:91], v[140:143], v[184:187], v[88:91]
	v_mfma_f32_16x16x32_bf16 v[84:87], v[132:135], v[192:195], v[84:87]
	v_mfma_f32_16x16x32_bf16 v[80:83], v[140:143], v[192:195], v[80:83]
	v_mfma_f32_16x16x32_bf16 v[76:79], v[132:135], v[200:203], v[76:79]
	v_mfma_f32_16x16x32_bf16 v[72:75], v[140:143], v[200:203], v[72:75]
	v_mfma_f32_16x16x32_bf16 v[68:71], v[132:135], v[234:237], v[68:71]
	v_mfma_f32_16x16x32_bf16 v[64:67], v[140:143], v[234:237], v[64:67]
	v_mfma_f32_16x16x32_bf16 v[28:31], v[164:167], v[180:183], v[28:31]
	v_mfma_f32_16x16x32_bf16 v[24:27], v[172:175], v[180:183], v[24:27]
	v_mfma_f32_16x16x32_bf16 v[20:23], v[164:167], v[188:191], v[20:23]
	v_mfma_f32_16x16x32_bf16 v[16:19], v[172:175], v[188:191], v[16:19]
	v_mfma_f32_16x16x32_bf16 v[12:15], v[164:167], v[196:199], v[12:15]
	v_mfma_f32_16x16x32_bf16 v[8:11], v[172:175], v[196:199], v[8:11]
	v_mfma_f32_16x16x32_bf16 v[4:7], v[164:167], v[230:233], v[4:7]
	v_mfma_f32_16x16x32_bf16 v[0:3], v[172:175], v[230:233], v[0:3]
	v_mfma_f32_16x16x32_bf16 v[28:31], v[168:171], v[184:187], v[28:31]
	v_mfma_f32_16x16x32_bf16 v[24:27], v[176:179], v[184:187], v[24:27]
	v_mfma_f32_16x16x32_bf16 v[20:23], v[168:171], v[192:195], v[20:23]
	v_mfma_f32_16x16x32_bf16 v[16:19], v[176:179], v[192:195], v[16:19]
	v_mfma_f32_16x16x32_bf16 v[12:15], v[168:171], v[200:203], v[12:15]
	v_mfma_f32_16x16x32_bf16 v[8:11], v[176:179], v[200:203], v[8:11]
	v_mfma_f32_16x16x32_bf16 v[4:7], v[168:171], v[234:237], v[4:7]
	v_mfma_f32_16x16x32_bf16 v[0:3], v[176:179], v[234:237], v[0:3]
	s_barrier
	s_setprio 0
	s_cmp_ge_u32 s48, s82
	s_mov_b32 s44, s48
	s_cbranch_scc0 .LBB0_132
	s_and_b64 vcc, exec, s[56:57]
	s_cbranch_vccz .LBB0_135
	s_barrier
